# GROPE GEMM: hand-written epilogue for RoPE tiles (8 shared cos/sin pairs loaded up front, counted vmcnt, stores never waited)
# speedup vs baseline: 1.0083x; 1.0083x over previous
; #define GM_WAIT_V(n) asm volatile("s_waitcnt vmcnt(" #n ")" ::: "memory")
; #define GM_WAIT_L(n) asm volatile("s_waitcnt lgkmcnt(" #n ")" ::: "memory")
; #define GM_BAR __builtin_amdgcn_s_barrier()
; #define GM_SCHED __builtin_amdgcn_sched_barrier(0)
; #define GM_LDA(dst, b, h) _Pragma("unroll") for (int m = 0; m < 4; ++m) _Pragma("unroll") for (int k = 0; k < 2; ++k) \
;         dst[m][k] = *(const LAS bf16x8*)(GM_SA(b, h) + aoff + (m * 2 + k) * 1024)
; #define GM_LDB(dst, b, h) _Pragma("unroll") for (int n = 0; n < 2; ++n) _Pragma("unroll") for (int k = 0; k < 2; ++k) \
;         dst[n][k] = *(const LAS bf16x8*)(GM_SB(b, h) + boff + (n * 2 + k) * 1024)
; #define GM_MMA(ai, bj, At, Bv) do { __builtin_amdgcn_s_setprio(1); \
;         _Pragma("unroll") for (int m = 0; m < 4; ++m) _Pragma("unroll") for (int n = 0; n < 2; ++n) _Pragma("unroll") for (int k = 0; k < 2; ++k) \
;             acc[ai][bj][m][n] = __builtin_amdgcn_mfma_f32_16x16x32_bf16(Bv[n][k], At[m][k], acc[ai][bj][m][n], 0, 0, 0); \
;         __builtin_amdgcn_s_setprio(0); } while (0)
; template <class Epi>
; __device__ __forceinline__ void gemm_phase(const bf16_t* __restrict__ A, const bf16_t* __restrict__ Bt, int M, int N, LAS unsigned char* lds, const Epi& epi, int vcu) {
;     ...
;         for (int t = 0; t < NT; t += 2) {
;             const bool lastk = (t + 2 >= NT);
;             const int prow = lastk ? nrow : brow, pcol = lastk ? ncol : bcol, k2 = lastk ? 0 : t + 2, k3 = lastk ? 1 : t + 3;
;             GM_LDB(B0, 0, 0); GM_SCHED; GM_LDA(At, 0, 0); GM_STAGE(GM_SA(1, 1), A, brow + HALF, t + 1);
;             GM_WAIT_L(8); GM_BAR; GM_WAIT_L(0); GM_MMA(0, 0, At, B0); GM_BAR; GM_SCHED;
;             GM_LDB(B1, 0, 1); GM_STAGE(GM_SB(0, 0), Bt, pcol, k2);
;             GM_BAR; GM_WAIT_L(0); GM_MMA(0, 1, At, B1); GM_BAR;
;             GM_LDA(At, 0, 1); GM_STAGE(GM_SA(0, 0), A, prow, k2);
;             GM_BAR; GM_WAIT_L(0); GM_MMA(1, 0, At, B0); GM_BAR; GM_SCHED;
;             GM_STAGE(GM_SB(0, 1), Bt, pcol + HALF, k2);
;             GM_WAIT_V(6); GM_BAR; GM_MMA(1, 1, At, B1); GM_BAR;
.LBB0_255:
	s_add_i32 s43, s43, 2
	v_add_u32_e32 v149, s88, v141
	s_cmp_gt_u32 s43, 13
	ds_read_b128 v[150:153], v149
	ds_read_b128 v[154:157], v149 offset:1024
	ds_read_b128 v[158:161], v149 offset:2048
	ds_read_b128 v[162:165], v149 offset:3072
	s_cselect_b64 s[54:55], -1, 0
	s_and_b64 s[54:55], s[54:55], exec
	s_cselect_b32 s54, 64, s45
	s_sub_i32 s10, s45, 64
	s_cmp_gt_u32 s43, 13
	s_cselect_b64 s[56:57], -1, 0
	s_and_b64 vcc, s[56:57], exec
	s_cselect_b32 s56, s5, s42
	s_cselect_b32 s58, s78, s44
	s_cselect_b32 s96, 0, s10
	v_add_u32_e32 v199, 0xc000, v133
	v_mov_b32_e32 v149, v1
	v_mov_b32_e32 v198, v130
	v_readfirstlane_b32 s10, v199
	ds_read_b128 v[166:169], v148
	ds_read_b128 v[170:173], v148 offset:1024
	ds_read_b128 v[174:177], v148 offset:2048
	ds_read_b128 v[178:181], v148 offset:3072
	ds_read_b128 v[182:185], v148 offset:4096
	ds_read_b128 v[186:189], v148 offset:5120
	ds_read_b128 v[190:193], v148 offset:6144
	ds_read_b128 v[194:197], v148 offset:7168
	s_mov_b32 m0, s10
	s_nop 0
	global_load_lds_dwordx4 v149, s[52:53]
	v_add_u32_e32 v149, 0xe000, v133
	s_nop 0
	v_readfirstlane_b32 s10, v149
	s_mov_b32 m0, s10
	s_nop 0
	global_load_lds_dwordx4 v198, s[52:53]
	s_waitcnt lgkmcnt(8)
	s_barrier
	s_waitcnt lgkmcnt(0)
	s_setprio 1
	s_waitcnt lgkmcnt(0)
	v_mfma_f32_16x16x32_bf16 v[126:129], v[150:153], v[166:169], v[126:129]
	v_mfma_f32_16x16x32_bf16 v[122:125], v[158:161], v[166:169], v[122:125]
	v_mfma_f32_16x16x32_bf16 v[110:113], v[150:153], v[174:177], v[110:113]
	v_mfma_f32_16x16x32_bf16 v[106:109], v[158:161], v[174:177], v[106:109]
	v_mfma_f32_16x16x32_bf16 v[94:97], v[150:153], v[182:185], v[94:97]
	v_mfma_f32_16x16x32_bf16 v[90:93], v[158:161], v[182:185], v[90:93]
	v_mfma_f32_16x16x32_bf16 v[78:81], v[150:153], v[190:193], v[78:81]
	v_mfma_f32_16x16x32_bf16 v[74:77], v[158:161], v[190:193], v[74:77]
	v_mfma_f32_16x16x32_bf16 v[126:129], v[154:157], v[170:173], v[126:129]
	v_mfma_f32_16x16x32_bf16 v[122:125], v[162:165], v[170:173], v[122:125]
	v_mfma_f32_16x16x32_bf16 v[110:113], v[154:157], v[178:181], v[110:113]
	v_mfma_f32_16x16x32_bf16 v[106:109], v[162:165], v[178:181], v[106:109]
	v_mfma_f32_16x16x32_bf16 v[94:97], v[154:157], v[186:189], v[94:97]
	v_mfma_f32_16x16x32_bf16 v[90:93], v[162:165], v[186:189], v[90:93]
	v_mfma_f32_16x16x32_bf16 v[78:81], v[154:157], v[194:197], v[78:81]
	v_mfma_f32_16x16x32_bf16 v[74:77], v[162:165], v[194:197], v[74:77]
	s_setprio 0
	s_barrier
	s_ashr_i32 s59, s58, 31
	s_lshl_b64 s[58:59], s[58:59], 11
	s_add_u32 s2, s51, s58
	s_addc_u32 s83, s34, s59
	s_lshl_b64 s[58:59], s[96:97], 1
	v_add_u32_e32 v149, s89, v141
	s_add_u32 s10, s2, s58
	v_readfirstlane_b32 s55, v131
	ds_read_b128 v[198:201], v149
	ds_read_b128 v[202:205], v149 offset:1024
	ds_read_b128 v[212:215], v149 offset:2048
	ds_read_b128 v[216:219], v149 offset:3072
	s_addc_u32 s11, s83, s59
	v_mov_b32_e32 v149, v1
	v_mov_b32_e32 v208, v130
	s_mov_b32 m0, s55
	v_readfirstlane_b32 s55, v132
	s_nop 0
	global_load_lds_dwordx4 v149, s[10:11]
	s_mov_b32 m0, s55
	s_nop 0
	global_load_lds_dwordx4 v208, s[10:11]
	s_barrier
	s_waitcnt lgkmcnt(0)
	s_setprio 1
	s_waitcnt lgkmcnt(0)
	v_mfma_f32_16x16x32_bf16 v[118:121], v[198:201], v[166:169], v[118:121]
	v_mfma_f32_16x16x32_bf16 v[114:117], v[212:215], v[166:169], v[114:117]
	v_mfma_f32_16x16x32_bf16 v[102:105], v[198:201], v[174:177], v[102:105]
	v_mfma_f32_16x16x32_bf16 v[98:101], v[212:215], v[174:177], v[98:101]
	v_mfma_f32_16x16x32_bf16 v[86:89], v[198:201], v[182:185], v[86:89]
	v_mfma_f32_16x16x32_bf16 v[82:85], v[212:215], v[182:185], v[82:85]
	v_mfma_f32_16x16x32_bf16 v[70:73], v[198:201], v[190:193], v[70:73]
	v_mfma_f32_16x16x32_bf16 v[66:69], v[212:215], v[190:193], v[66:69]
	v_mfma_f32_16x16x32_bf16 v[118:121], v[202:205], v[170:173], v[118:121]
	v_mfma_f32_16x16x32_bf16 v[114:117], v[216:219], v[170:173], v[114:117]
	v_mfma_f32_16x16x32_bf16 v[102:105], v[202:205], v[178:181], v[102:105]
	v_mfma_f32_16x16x32_bf16 v[98:101], v[216:219], v[178:181], v[98:101]
	v_mfma_f32_16x16x32_bf16 v[86:89], v[202:205], v[186:189], v[86:89]
	v_mfma_f32_16x16x32_bf16 v[82:85], v[216:219], v[186:189], v[82:85]
	v_mfma_f32_16x16x32_bf16 v[70:73], v[202:205], v[194:197], v[70:73]
	v_mfma_f32_16x16x32_bf16 v[66:69], v[216:219], v[194:197], v[66:69]
	s_setprio 0
	s_ashr_i32 s57, s56, 31
	s_lshl_b64 s[10:11], s[56:57], 11
	s_add_u32 s96, s14, s10
	s_addc_u32 s36, s15, s11
	s_add_u32 s10, s96, s58
	v_readfirstlane_b32 s55, v133
	s_addc_u32 s11, s36, s59
	v_mov_b32_e32 v149, v1
	v_mov_b32_e32 v208, v130
	s_mov_b32 m0, s55
	v_readfirstlane_b32 s55, v134
	s_barrier
	ds_read_b128 v[166:169], v148 offset:16384
	ds_read_b128 v[170:173], v148 offset:17408
	ds_read_b128 v[174:177], v148 offset:18432
	ds_read_b128 v[178:181], v148 offset:19456
	ds_read_b128 v[182:185], v148 offset:20480
	ds_read_b128 v[186:189], v148 offset:21504
	ds_read_b128 v[190:193], v148 offset:22528
	ds_read_b128 v[194:197], v148 offset:23552
	s_nop 0
	global_load_lds_dwordx4 v149, s[10:11]
	s_mov_b32 m0, s55
	s_nop 0
	global_load_lds_dwordx4 v208, s[10:11]
	s_barrier
; #define GM_WAIT_V(n) asm volatile("s_waitcnt vmcnt(" #n ")" ::: "memory")
; #define GM_WAIT_L(n) asm volatile("s_waitcnt lgkmcnt(" #n ")" ::: "memory")
; #define GM_BAR __builtin_amdgcn_s_barrier()
; #define GM_SCHED __builtin_amdgcn_sched_barrier(0)
; #define GM_LDA(dst, b, h) _Pragma("unroll") for (int m = 0; m < 4; ++m) _Pragma("unroll") for (int k = 0; k < 2; ++k) \
;         dst[m][k] = *(const LAS bf16x8*)(GM_SA(b, h) + aoff + (m * 2 + k) * 1024)
; #define GM_LDB(dst, b, h) _Pragma("unroll") for (int n = 0; n < 2; ++n) _Pragma("unroll") for (int k = 0; k < 2; ++k) \
;         dst[n][k] = *(const LAS bf16x8*)(GM_SB(b, h) + boff + (n * 2 + k) * 1024)
; #define GM_MMA(ai, bj, At, Bv) do { __builtin_amdgcn_s_setprio(1); \
;         _Pragma("unroll") for (int m = 0; m < 4; ++m) _Pragma("unroll") for (int n = 0; n < 2; ++n) _Pragma("unroll") for (int k = 0; k < 2; ++k) \
;             acc[ai][bj][m][n] = __builtin_amdgcn_mfma_f32_16x16x32_bf16(Bv[n][k], At[m][k], acc[ai][bj][m][n], 0, 0, 0); \
;         __builtin_amdgcn_s_setprio(0); } while (0)
; template <class Epi>
; __device__ __forceinline__ void gemm_phase(const bf16_t* __restrict__ A, const bf16_t* __restrict__ Bt, int M, int N, LAS unsigned char* lds, const Epi& epi, int vcu) {
;     ...
;             GM_STAGE(GM_SB(0, 1), Bt, pcol + HALF, k2);
;             GM_WAIT_V(6); GM_BAR; GM_MMA(1, 1, At, B1); GM_BAR;
;             GM_LDB(B0, 1, 0); GM_SCHED; GM_LDA(At, 1, 0); GM_STAGE(GM_SA(0, 1), A, prow + HALF, k2);
;             GM_WAIT_L(8); GM_BAR; GM_WAIT_L(0); GM_MMA(0, 0, At, B0); GM_BAR; GM_SCHED;
;             GM_LDB(B1, 1, 1); GM_STAGE(GM_SB(1, 0), Bt, pcol, k3);
;             GM_BAR; GM_WAIT_L(0); GM_MMA(0, 1, At, B1); GM_BAR;
;             GM_LDA(At, 1, 1); GM_STAGE(GM_SA(1, 0), A, prow, k3);
;             GM_BAR; GM_WAIT_L(0); GM_MMA(1, 0, At, B0); GM_BAR; GM_SCHED;
	s_waitcnt lgkmcnt(0)
	s_setprio 1
	s_waitcnt lgkmcnt(0)
	v_mfma_f32_16x16x32_bf16 v[62:65], v[150:153], v[166:169], v[62:65]
	v_mfma_f32_16x16x32_bf16 v[58:61], v[158:161], v[166:169], v[58:61]
	v_mfma_f32_16x16x32_bf16 v[46:49], v[150:153], v[174:177], v[46:49]
	v_mfma_f32_16x16x32_bf16 v[42:45], v[158:161], v[174:177], v[42:45]
	v_mfma_f32_16x16x32_bf16 v[30:33], v[150:153], v[182:185], v[30:33]
	v_mfma_f32_16x16x32_bf16 v[26:29], v[158:161], v[182:185], v[26:29]
	v_mfma_f32_16x16x32_bf16 v[14:17], v[150:153], v[190:193], v[14:17]
	v_mfma_f32_16x16x32_bf16 v[10:13], v[158:161], v[190:193], v[10:13]
	v_mfma_f32_16x16x32_bf16 v[62:65], v[154:157], v[170:173], v[62:65]
	v_mfma_f32_16x16x32_bf16 v[58:61], v[162:165], v[170:173], v[58:61]
	v_mfma_f32_16x16x32_bf16 v[46:49], v[154:157], v[178:181], v[46:49]
	v_mfma_f32_16x16x32_bf16 v[42:45], v[162:165], v[178:181], v[42:45]
	v_mfma_f32_16x16x32_bf16 v[30:33], v[154:157], v[186:189], v[30:33]
	v_mfma_f32_16x16x32_bf16 v[26:29], v[162:165], v[186:189], v[26:29]
	v_mfma_f32_16x16x32_bf16 v[14:17], v[154:157], v[194:197], v[14:17]
	v_mfma_f32_16x16x32_bf16 v[10:13], v[162:165], v[194:197], v[10:13]
	s_setprio 0
	s_barrier
	s_add_u32 s35, s2, 0x40000
	s_addc_u32 s70, s83, 0
	s_add_u32 s56, s35, s58
	v_readfirstlane_b32 s55, v135
	s_addc_u32 s57, s70, s59
	v_mov_b32_e32 v149, v1
	v_mov_b32_e32 v150, v130
	s_mov_b32 m0, s55
	v_readfirstlane_b32 s55, v136
	s_nop 0
	global_load_lds_dwordx4 v149, s[56:57]
	s_mov_b32 m0, s55
	s_nop 0
	global_load_lds_dwordx4 v150, s[56:57]
	s_waitcnt vmcnt(6)
	s_barrier
	s_setprio 1
	v_mfma_f32_16x16x32_bf16 v[54:57], v[198:201], v[166:169], v[54:57]
	v_mfma_f32_16x16x32_bf16 v[50:53], v[212:215], v[166:169], v[50:53]
	v_mfma_f32_16x16x32_bf16 v[38:41], v[198:201], v[174:177], v[38:41]
	v_mfma_f32_16x16x32_bf16 v[34:37], v[212:215], v[174:177], v[34:37]
	v_mfma_f32_16x16x32_bf16 v[22:25], v[198:201], v[182:185], v[22:25]
	v_mfma_f32_16x16x32_bf16 v[18:21], v[212:215], v[182:185], v[18:21]
	v_mfma_f32_16x16x32_bf16 v[6:9], v[198:201], v[190:193], v[6:9]
	v_mfma_f32_16x16x32_bf16 v[2:5], v[212:215], v[190:193], v[2:5]
	v_mfma_f32_16x16x32_bf16 v[54:57], v[202:205], v[170:173], v[54:57]
	v_mfma_f32_16x16x32_bf16 v[50:53], v[216:219], v[170:173], v[50:53]
	v_mfma_f32_16x16x32_bf16 v[38:41], v[202:205], v[178:181], v[38:41]
	v_mfma_f32_16x16x32_bf16 v[34:37], v[216:219], v[178:181], v[34:37]
	v_mfma_f32_16x16x32_bf16 v[22:25], v[202:205], v[186:189], v[22:25]
	v_mfma_f32_16x16x32_bf16 v[18:21], v[216:219], v[186:189], v[18:21]
	v_mfma_f32_16x16x32_bf16 v[6:9], v[202:205], v[194:197], v[6:9]
	v_mfma_f32_16x16x32_bf16 v[2:5], v[216:219], v[194:197], v[2:5]
	s_setprio 0
	v_add_u32_e32 v149, s16, v141
	s_barrier
	ds_read_b128 v[150:153], v149
	ds_read_b128 v[154:157], v149 offset:1024
	ds_read_b128 v[158:161], v149 offset:2048
	ds_read_b128 v[162:165], v149 offset:3072
	s_add_u32 s10, s10, 0x40000
	v_readfirstlane_b32 s55, v137
	s_addc_u32 s11, s11, 0
	v_mov_b32_e32 v149, v1
	v_mov_b32_e32 v198, v130
	s_mov_b32 m0, s55
	v_readfirstlane_b32 s55, v138
	ds_read_b128 v[166:169], v148 offset:32768
	ds_read_b128 v[170:173], v148 offset:33792
	ds_read_b128 v[174:177], v148 offset:34816
	ds_read_b128 v[178:181], v148 offset:35840
	ds_read_b128 v[182:185], v148 offset:36864
	ds_read_b128 v[186:189], v148 offset:37888
	ds_read_b128 v[190:193], v148 offset:38912
	ds_read_b128 v[194:197], v148 offset:39936
	s_nop 0
	global_load_lds_dwordx4 v149, s[10:11]
	s_mov_b32 m0, s55
	s_nop 0
	global_load_lds_dwordx4 v198, s[10:11]
	s_waitcnt lgkmcnt(8)
	s_barrier
	s_waitcnt lgkmcnt(0)
	s_setprio 1
	s_waitcnt lgkmcnt(0)
	v_mfma_f32_16x16x32_bf16 v[126:129], v[150:153], v[166:169], v[126:129]
	v_mfma_f32_16x16x32_bf16 v[122:125], v[158:161], v[166:169], v[122:125]
	v_mfma_f32_16x16x32_bf16 v[110:113], v[150:153], v[174:177], v[110:113]
	v_mfma_f32_16x16x32_bf16 v[106:109], v[158:161], v[174:177], v[106:109]
	v_mfma_f32_16x16x32_bf16 v[94:97], v[150:153], v[182:185], v[94:97]
	v_mfma_f32_16x16x32_bf16 v[90:93], v[158:161], v[182:185], v[90:93]
	v_mfma_f32_16x16x32_bf16 v[78:81], v[150:153], v[190:193], v[78:81]
	v_mfma_f32_16x16x32_bf16 v[74:77], v[158:161], v[190:193], v[74:77]
	v_mfma_f32_16x16x32_bf16 v[126:129], v[154:157], v[170:173], v[126:129]
	v_mfma_f32_16x16x32_bf16 v[122:125], v[162:165], v[170:173], v[122:125]
	v_mfma_f32_16x16x32_bf16 v[110:113], v[154:157], v[178:181], v[110:113]
	v_mfma_f32_16x16x32_bf16 v[106:109], v[162:165], v[178:181], v[106:109]
	v_mfma_f32_16x16x32_bf16 v[94:97], v[154:157], v[186:189], v[94:97]
	v_mfma_f32_16x16x32_bf16 v[90:93], v[162:165], v[186:189], v[90:93]
	v_mfma_f32_16x16x32_bf16 v[78:81], v[154:157], v[194:197], v[78:81]
	v_mfma_f32_16x16x32_bf16 v[74:77], v[162:165], v[194:197], v[74:77]
	s_setprio 0
	s_barrier
	s_mov_b32 s55, s97
	s_lshl_b64 s[10:11], s[54:55], 1
	v_add_u32_e32 v149, s17, v141
	s_add_u32 s54, s2, s10
	v_readfirstlane_b32 s2, v142
	ds_read_b128 v[198:201], v149
	ds_read_b128 v[202:205], v149 offset:1024
	ds_read_b128 v[212:215], v149 offset:2048
	ds_read_b128 v[216:219], v149 offset:3072
	s_addc_u32 s55, s83, s11
	v_mov_b32_e32 v149, v1
	v_mov_b32_e32 v208, v130
	s_mov_b32 m0, s2
	v_readfirstlane_b32 s2, v143
	s_nop 0
	global_load_lds_dwordx4 v149, s[54:55]
	s_mov_b32 m0, s2
	s_nop 0
	global_load_lds_dwordx4 v208, s[54:55]
	s_barrier
; #define GM_WAIT_V(n) asm volatile("s_waitcnt vmcnt(" #n ")" ::: "memory")
; #define GM_WAIT_L(n) asm volatile("s_waitcnt lgkmcnt(" #n ")" ::: "memory")
; #define GM_BAR __builtin_amdgcn_s_barrier()
; #define GM_SCHED __builtin_amdgcn_sched_barrier(0)
; #define GM_LDA(dst, b, h) _Pragma("unroll") for (int m = 0; m < 4; ++m) _Pragma("unroll") for (int k = 0; k < 2; ++k) \
;         dst[m][k] = *(const LAS bf16x8*)(GM_SA(b, h) + aoff + (m * 2 + k) * 1024)
; #define GM_LDB(dst, b, h) _Pragma("unroll") for (int n = 0; n < 2; ++n) _Pragma("unroll") for (int k = 0; k < 2; ++k) \
;         dst[n][k] = *(const LAS bf16x8*)(GM_SB(b, h) + boff + (n * 2 + k) * 1024)
; #define GM_MMA(ai, bj, At, Bv) do { __builtin_amdgcn_s_setprio(1); \
;         _Pragma("unroll") for (int m = 0; m < 4; ++m) _Pragma("unroll") for (int n = 0; n < 2; ++n) _Pragma("unroll") for (int k = 0; k < 2; ++k) \
;             acc[ai][bj][m][n] = __builtin_amdgcn_mfma_f32_16x16x32_bf16(Bv[n][k], At[m][k], acc[ai][bj][m][n], 0, 0, 0); \
;         __builtin_amdgcn_s_setprio(0); } while (0)
; template <class Epi>
; __device__ __forceinline__ void gemm_phase(const bf16_t* __restrict__ A, const bf16_t* __restrict__ Bt, int M, int N, LAS unsigned char* lds, const Epi& epi, int vcu) {
;     ...
;             GM_WAIT_L(8); GM_BAR; GM_WAIT_L(0); GM_MMA(0, 0, At, B0); GM_BAR; GM_SCHED;
;             GM_LDB(B1, 1, 1); GM_STAGE(GM_SB(1, 0), Bt, pcol, k3);
;             GM_BAR; GM_WAIT_L(0); GM_MMA(0, 1, At, B1); GM_BAR;
;             GM_LDA(At, 1, 1); GM_STAGE(GM_SA(1, 0), A, prow, k3);
;             GM_BAR; GM_WAIT_L(0); GM_MMA(1, 0, At, B0); GM_BAR; GM_SCHED;
;             GM_STAGE(GM_SB(1, 1), Bt, pcol + HALF, k3);
;             GM_WAIT_V(6); GM_BAR; GM_MMA(1, 1, At, B1); GM_BAR;
;         }
;     ...
;                     for (int bj = 0; bj < 2; ++bj) { const int m = mp * 2 + mq;
;                         epi(brow + ai * HALF + wr * 64 + m * 16 + fre, (bcol + bj * HALF + wc * 32) >> 5, fqe, acc[ai][bj][m][0], acc[ai][bj][m][1]); }
	s_waitcnt lgkmcnt(0)
	s_setprio 1
	s_waitcnt lgkmcnt(0)
	v_mfma_f32_16x16x32_bf16 v[118:121], v[198:201], v[166:169], v[118:121]
	v_mfma_f32_16x16x32_bf16 v[114:117], v[212:215], v[166:169], v[114:117]
	v_mfma_f32_16x16x32_bf16 v[102:105], v[198:201], v[174:177], v[102:105]
	v_mfma_f32_16x16x32_bf16 v[98:101], v[212:215], v[174:177], v[98:101]
	v_mfma_f32_16x16x32_bf16 v[86:89], v[198:201], v[182:185], v[86:89]
	v_mfma_f32_16x16x32_bf16 v[82:85], v[212:215], v[182:185], v[82:85]
	v_mfma_f32_16x16x32_bf16 v[70:73], v[198:201], v[190:193], v[70:73]
	v_mfma_f32_16x16x32_bf16 v[66:69], v[212:215], v[190:193], v[66:69]
	v_mfma_f32_16x16x32_bf16 v[118:121], v[202:205], v[170:173], v[118:121]
	v_mfma_f32_16x16x32_bf16 v[114:117], v[216:219], v[170:173], v[114:117]
	v_mfma_f32_16x16x32_bf16 v[102:105], v[202:205], v[178:181], v[102:105]
	v_mfma_f32_16x16x32_bf16 v[98:101], v[216:219], v[178:181], v[98:101]
	v_mfma_f32_16x16x32_bf16 v[86:89], v[202:205], v[186:189], v[86:89]
	v_mfma_f32_16x16x32_bf16 v[82:85], v[216:219], v[186:189], v[82:85]
	v_mfma_f32_16x16x32_bf16 v[70:73], v[202:205], v[194:197], v[70:73]
	v_mfma_f32_16x16x32_bf16 v[66:69], v[216:219], v[194:197], v[66:69]
	s_setprio 0
	s_add_u32 s54, s96, s10
	v_readfirstlane_b32 s2, v144
	s_addc_u32 s55, s36, s11
	v_mov_b32_e32 v149, v1
	v_mov_b32_e32 v208, v130
	s_mov_b32 m0, s2
	v_readfirstlane_b32 s2, v145
	s_barrier
	ds_read_b128 v[166:169], v148 offset:49152
	ds_read_b128 v[170:173], v148 offset:50176
	ds_read_b128 v[174:177], v148 offset:51200
	ds_read_b128 v[178:181], v148 offset:52224
	ds_read_b128 v[182:185], v148 offset:53248
	ds_read_b128 v[186:189], v148 offset:54272
	ds_read_b128 v[190:193], v148 offset:55296
	ds_read_b128 v[194:197], v148 offset:56320
	s_nop 0
	global_load_lds_dwordx4 v149, s[54:55]
	s_mov_b32 m0, s2
	s_nop 0
	global_load_lds_dwordx4 v208, s[54:55]
	s_barrier
	s_waitcnt lgkmcnt(0)
	s_setprio 1
	s_waitcnt lgkmcnt(0)
	v_mfma_f32_16x16x32_bf16 v[62:65], v[150:153], v[166:169], v[62:65]
	v_mfma_f32_16x16x32_bf16 v[58:61], v[158:161], v[166:169], v[58:61]
	v_mfma_f32_16x16x32_bf16 v[46:49], v[150:153], v[174:177], v[46:49]
	v_mfma_f32_16x16x32_bf16 v[42:45], v[158:161], v[174:177], v[42:45]
	v_mfma_f32_16x16x32_bf16 v[30:33], v[150:153], v[182:185], v[30:33]
	v_mfma_f32_16x16x32_bf16 v[26:29], v[158:161], v[182:185], v[26:29]
	v_mfma_f32_16x16x32_bf16 v[14:17], v[150:153], v[190:193], v[14:17]
	v_mfma_f32_16x16x32_bf16 v[10:13], v[158:161], v[190:193], v[10:13]
	v_mfma_f32_16x16x32_bf16 v[62:65], v[154:157], v[170:173], v[62:65]
	v_mfma_f32_16x16x32_bf16 v[58:61], v[162:165], v[170:173], v[58:61]
	v_mfma_f32_16x16x32_bf16 v[46:49], v[154:157], v[178:181], v[46:49]
	v_mfma_f32_16x16x32_bf16 v[42:45], v[162:165], v[178:181], v[42:45]
	v_mfma_f32_16x16x32_bf16 v[30:33], v[154:157], v[186:189], v[30:33]
	v_mfma_f32_16x16x32_bf16 v[26:29], v[162:165], v[186:189], v[26:29]
	v_mfma_f32_16x16x32_bf16 v[14:17], v[154:157], v[194:197], v[14:17]
	v_mfma_f32_16x16x32_bf16 v[10:13], v[162:165], v[194:197], v[10:13]
	s_setprio 0
	s_barrier
	s_add_u32 s10, s35, s10
	v_readfirstlane_b32 s2, v146
	s_addc_u32 s11, s70, s11
	v_mov_b32_e32 v149, v1
	v_mov_b32_e32 v150, v130
	s_mov_b32 m0, s2
	v_readfirstlane_b32 s2, v147
	s_nop 0
	global_load_lds_dwordx4 v149, s[10:11]
	s_mov_b32 m0, s2
	s_nop 0
	global_load_lds_dwordx4 v150, s[10:11]
	s_waitcnt vmcnt(6)
	s_barrier
	s_setprio 1
	v_mfma_f32_16x16x32_bf16 v[54:57], v[198:201], v[166:169], v[54:57]
	v_mfma_f32_16x16x32_bf16 v[50:53], v[212:215], v[166:169], v[50:53]
	v_mfma_f32_16x16x32_bf16 v[38:41], v[198:201], v[174:177], v[38:41]
	v_mfma_f32_16x16x32_bf16 v[34:37], v[212:215], v[174:177], v[34:37]
	v_mfma_f32_16x16x32_bf16 v[22:25], v[198:201], v[182:185], v[22:25]
	v_mfma_f32_16x16x32_bf16 v[18:21], v[212:215], v[182:185], v[18:21]
	v_mfma_f32_16x16x32_bf16 v[6:9], v[198:201], v[190:193], v[6:9]
	v_mfma_f32_16x16x32_bf16 v[2:5], v[212:215], v[190:193], v[2:5]
	v_mfma_f32_16x16x32_bf16 v[54:57], v[202:205], v[170:173], v[54:57]
	v_mfma_f32_16x16x32_bf16 v[50:53], v[216:219], v[170:173], v[50:53]
	v_mfma_f32_16x16x32_bf16 v[38:41], v[202:205], v[178:181], v[38:41]
	v_mfma_f32_16x16x32_bf16 v[34:37], v[216:219], v[178:181], v[34:37]
	v_mfma_f32_16x16x32_bf16 v[22:25], v[202:205], v[186:189], v[22:25]
	v_mfma_f32_16x16x32_bf16 v[18:21], v[216:219], v[186:189], v[18:21]
	v_mfma_f32_16x16x32_bf16 v[6:9], v[202:205], v[194:197], v[6:9]
	v_mfma_f32_16x16x32_bf16 v[2:5], v[216:219], v[194:197], v[2:5]
	s_setprio 0
	s_addk_i32 s45, 0x80
	s_add_u32 s52, s52, 0x100
	s_addc_u32 s53, s53, 0
	s_barrier
	s_cbranch_vccz .LBB0_255
	s_cmp_lt_i32 s44, s21
	s_cbranch_scc1 .Lre_entry
	s_add_i32 s56, s44, s66
	s_add_i32 s10, s42, s65
	s_and_b32 s55, s56, 0xffffffe0
	v_mov_b32_e32 v149, v139
	v_mov_b32_e32 v150, v140
	s_cmp_ge_i32 s55, s21
	s_cselect_b64 s[42:43], -1, 0
	v_add_u32_e32 v151, s10, v149
	v_lshlrev_b32_e32 v149, 3, v150
	v_mul_lo_u32 v152, v151, s79
	s_mov_b64 s[44:45], -1
	s_and_b64 vcc, exec, s[42:43]
	s_cbranch_vccz .LBB0_258
	v_add3_u32 v158, v149, s55, v152
	v_mov_b32_e32 v159, v0
	v_cvt_pk_bf16_f32 v154, v126, v127
	v_cvt_pk_bf16_f32 v155, v128, v129
	v_cvt_pk_bf16_f32 v156, v122, v123
	v_cvt_pk_bf16_f32 v157, v124, v125
	v_lshl_add_u64 v[158:159], v[158:159], 1, s[76:77]
	global_store_dwordx4 v[158:159], v[154:157], off
	s_mov_b64 s[44:45], 0

; __device__ __forceinline__ unsigned pk_bf16(float lo, float hi) { const f32x2 v = {lo, hi}; const bf16v2 b = __builtin_convertvector(v, bf16v2); return __builtin_bit_cast(unsigned, b); }
;     __device__ __forceinline__ void operator()(int row, int G, int fq, f32x4 v0, f32x4 v1) const {
;         const int col32 = G * 32;
;         const unsigned ro = (unsigned)row * (unsigned)ld;
;         if (col32 < rope_end) {
;             const int half = hd >> 1, hb = col32 & ~(hd - 1), d0 = ((col32 & (hd - 1)) >> 5) * 16 + fq * 4, pos = row & (SEQ - 1);
;             const unsigned to = (unsigned)(pos * half + d0);
;             const f32x4 c = *(const f32x4*)(cosT + to), s = *(const f32x4*)(sinT + to);
;             const f32x4 o1 = v0 * c - v1 * s, o2 = v1 * c + v0 * s;
;             u32x2 w1, w2; w1.x = pk_bf16(o1[0], o1[1]); w1.y = pk_bf16(o1[2], o1[3]); w2.x = pk_bf16(o2[0], o2[1]); w2.y = pk_bf16(o2[2], o2[3]);
;             *(u32x2*)(out + (ro + (unsigned)(hb + d0))) = w1; *(u32x2*)(out + (ro + (unsigned)(hb + half + d0))) = w2;
.Lre_entry:
	s_add_i32 s56, s44, s66
	s_and_b32 s2, s56, s28
	s_lshr_b32 s2, s2, 1
	s_and_b32 s10, s56, s37
	s_add_i32 s10, s10, s2
	s_add_i32 s11, s42, s65
	v_add_u32_e32 v149, s11, v139
	v_lshlrev_b32_e32 v212, 2, v140
	v_and_b32_e32 v213, 0x1fff, v149
	v_add_u32_e32 v214, s2, v212
	v_mad_u32_u24 v213, v213, s67, v214
	v_lshlrev_b32_e32 v213, 2, v213
	v_mul_lo_u32 v215, v149, s79
	v_add3_u32 v215, v215, s10, v212
	v_lshlrev_b32_e32 v215, 1, v215
	v_lshl_add_u32 v212, s67, 1, v215
	s_lshl_b32 s2, s67, 6
	s_mul_i32 s56, s2, 5
	s_lshl_b32 s10, s79, 5
	s_mul_i32 s11, s10, 5
	s_mov_b64 s[52:53], s[46:47]
	s_mov_b64 s[54:55], s[26:27]
	s_mov_b64 s[42:43], s[76:77]
	global_load_dwordx4 v[150:153], v213, s[52:53]
	global_load_dwordx4 v[154:157], v213, s[54:55]
	s_add_u32 s52, s52, s2
	s_addc_u32 s53, s53, 0
	s_add_u32 s54, s54, s2
	s_addc_u32 s55, s55, 0
	global_load_dwordx4 v[158:161], v213, s[52:53]
	global_load_dwordx4 v[162:165], v213, s[54:55]
	s_add_u32 s52, s52, s2
	s_addc_u32 s53, s53, 0
	s_add_u32 s54, s54, s2
	s_addc_u32 s55, s55, 0
	global_load_dwordx4 v[166:169], v213, s[52:53]
	global_load_dwordx4 v[170:173], v213, s[54:55]
	s_add_u32 s52, s52, s2
	s_addc_u32 s53, s53, 0
	s_add_u32 s54, s54, s2
	s_addc_u32 s55, s55, 0
	global_load_dwordx4 v[174:177], v213, s[52:53]
	global_load_dwordx4 v[178:181], v213, s[54:55]
	s_add_u32 s52, s52, s56
	s_addc_u32 s53, s53, 0
	s_add_u32 s54, s54, s56
	s_addc_u32 s55, s55, 0
	global_load_dwordx4 v[182:185], v213, s[52:53]
	global_load_dwordx4 v[186:189], v213, s[54:55]
	s_add_u32 s52, s52, s2
	s_addc_u32 s53, s53, 0
	s_add_u32 s54, s54, s2
	s_addc_u32 s55, s55, 0
	global_load_dwordx4 v[190:193], v213, s[52:53]
	global_load_dwordx4 v[194:197], v213, s[54:55]
	s_add_u32 s52, s52, s2
	s_addc_u32 s53, s53, 0
	s_add_u32 s54, s54, s2
	s_addc_u32 s55, s55, 0
	s_waitcnt vmcnt(10)
	v_pk_mul_f32 v[218:219], v[122:123], v[154:155]
	v_pk_mul_f32 v[216:217], v[126:127], v[154:155]
	v_pk_fma_f32 v[122:123], v[122:123], v[150:151], v[216:217]
	v_pk_fma_f32 v[126:127], v[126:127], v[150:151], v[218:219] neg_lo:[0,0,1] neg_hi:[0,0,1]
	v_pk_mul_f32 v[218:219], v[124:125], v[156:157]
	v_pk_mul_f32 v[216:217], v[128:129], v[156:157]
	v_pk_fma_f32 v[124:125], v[124:125], v[152:153], v[216:217]
	v_pk_fma_f32 v[128:129], v[128:129], v[152:153], v[218:219] neg_lo:[0,0,1] neg_hi:[0,0,1]
	v_cvt_pk_bf16_f32 v126, v126, v127
	v_cvt_pk_bf16_f32 v127, v128, v129
	v_cvt_pk_bf16_f32 v122, v122, v123
	v_cvt_pk_bf16_f32 v123, v124, v125
	global_store_dwordx2 v215, v[126:127], s[42:43]
	global_store_dwordx2 v212, v[122:123], s[42:43]
	v_pk_mul_f32 v[218:219], v[114:115], v[154:155]
	v_pk_mul_f32 v[216:217], v[118:119], v[154:155]
	v_pk_fma_f32 v[114:115], v[114:115], v[150:151], v[216:217]
	v_pk_fma_f32 v[118:119], v[118:119], v[150:151], v[218:219] neg_lo:[0,0,1] neg_hi:[0,0,1]
	v_pk_mul_f32 v[218:219], v[116:117], v[156:157]
	v_pk_mul_f32 v[216:217], v[120:121], v[156:157]
	v_pk_fma_f32 v[116:117], v[116:117], v[152:153], v[216:217]
	v_pk_fma_f32 v[120:121], v[120:121], v[152:153], v[218:219] neg_lo:[0,0,1] neg_hi:[0,0,1]
	v_cvt_pk_bf16_f32 v118, v118, v119
	v_cvt_pk_bf16_f32 v119, v120, v121
	v_cvt_pk_bf16_f32 v114, v114, v115
	v_cvt_pk_bf16_f32 v115, v116, v117
	global_store_dwordx2 v215, v[118:119], s[42:43] offset:256
	global_store_dwordx2 v212, v[114:115], s[42:43] offset:256
	s_add_u32 s42, s42, s10
	s_addc_u32 s43, s43, 0
	s_waitcnt vmcnt(12)
	v_pk_mul_f32 v[218:219], v[106:107], v[162:163]
	v_pk_mul_f32 v[216:217], v[110:111], v[162:163]
	v_pk_fma_f32 v[106:107], v[106:107], v[158:159], v[216:217]
	v_pk_fma_f32 v[110:111], v[110:111], v[158:159], v[218:219] neg_lo:[0,0,1] neg_hi:[0,0,1]
	v_pk_mul_f32 v[218:219], v[108:109], v[164:165]
	v_pk_mul_f32 v[216:217], v[112:113], v[164:165]
	v_pk_fma_f32 v[108:109], v[108:109], v[160:161], v[216:217]
	v_pk_fma_f32 v[112:113], v[112:113], v[160:161], v[218:219] neg_lo:[0,0,1] neg_hi:[0,0,1]
	v_cvt_pk_bf16_f32 v110, v110, v111
	v_cvt_pk_bf16_f32 v111, v112, v113
	v_cvt_pk_bf16_f32 v106, v106, v107
	v_cvt_pk_bf16_f32 v107, v108, v109
	global_store_dwordx2 v215, v[110:111], s[42:43]
	global_store_dwordx2 v212, v[106:107], s[42:43]
	v_pk_mul_f32 v[218:219], v[98:99], v[162:163]
	v_pk_mul_f32 v[216:217], v[102:103], v[162:163]
	v_pk_fma_f32 v[98:99], v[98:99], v[158:159], v[216:217]
	v_pk_fma_f32 v[102:103], v[102:103], v[158:159], v[218:219] neg_lo:[0,0,1] neg_hi:[0,0,1]
	v_pk_mul_f32 v[218:219], v[100:101], v[164:165]
	v_pk_mul_f32 v[216:217], v[104:105], v[164:165]
	v_pk_fma_f32 v[100:101], v[100:101], v[160:161], v[216:217]
	v_pk_fma_f32 v[104:105], v[104:105], v[160:161], v[218:219] neg_lo:[0,0,1] neg_hi:[0,0,1]
	v_cvt_pk_bf16_f32 v102, v102, v103
	v_cvt_pk_bf16_f32 v103, v104, v105
	v_cvt_pk_bf16_f32 v98, v98, v99
	v_cvt_pk_bf16_f32 v99, v100, v101
	global_store_dwordx2 v215, v[102:103], s[42:43] offset:256
	global_store_dwordx2 v212, v[98:99], s[42:43] offset:256
	s_add_u32 s42, s42, s10
	s_addc_u32 s43, s43, 0
	global_load_dwordx4 v[150:153], v213, s[52:53]
	global_load_dwordx4 v[154:157], v213, s[54:55]
	s_add_u32 s52, s52, s2
	s_addc_u32 s53, s53, 0
	s_add_u32 s54, s54, s2
	s_addc_u32 s55, s55, 0
	global_load_dwordx4 v[158:161], v213, s[52:53]
	global_load_dwordx4 v[162:165], v213, s[54:55]
	s_waitcnt vmcnt(18)
; __device__ __forceinline__ unsigned pk_bf16(float lo, float hi) { const f32x2 v = {lo, hi}; const bf16v2 b = __builtin_convertvector(v, bf16v2); return __builtin_bit_cast(unsigned, b); }
;     __device__ __forceinline__ void operator()(int row, int G, int fq, f32x4 v0, f32x4 v1) const {
;         const int col32 = G * 32;
;         const unsigned ro = (unsigned)row * (unsigned)ld;
;         if (col32 < rope_end) {
;             const int half = hd >> 1, hb = col32 & ~(hd - 1), d0 = ((col32 & (hd - 1)) >> 5) * 16 + fq * 4, pos = row & (SEQ - 1);
;             const unsigned to = (unsigned)(pos * half + d0);
;             const f32x4 c = *(const f32x4*)(cosT + to), s = *(const f32x4*)(sinT + to);
;             const f32x4 o1 = v0 * c - v1 * s, o2 = v1 * c + v0 * s;
;             u32x2 w1, w2; w1.x = pk_bf16(o1[0], o1[1]); w1.y = pk_bf16(o1[2], o1[3]); w2.x = pk_bf16(o2[0], o2[1]); w2.y = pk_bf16(o2[2], o2[3]);
;             *(u32x2*)(out + (ro + (unsigned)(hb + d0))) = w1; *(u32x2*)(out + (ro + (unsigned)(hb + half + d0))) = w2;
	v_pk_mul_f32 v[218:219], v[90:91], v[170:171]
	v_pk_mul_f32 v[216:217], v[94:95], v[170:171]
	v_pk_fma_f32 v[90:91], v[90:91], v[166:167], v[216:217]
	v_pk_fma_f32 v[94:95], v[94:95], v[166:167], v[218:219] neg_lo:[0,0,1] neg_hi:[0,0,1]
	v_pk_mul_f32 v[218:219], v[92:93], v[172:173]
	v_pk_mul_f32 v[216:217], v[96:97], v[172:173]
	v_pk_fma_f32 v[92:93], v[92:93], v[168:169], v[216:217]
	v_pk_fma_f32 v[96:97], v[96:97], v[168:169], v[218:219] neg_lo:[0,0,1] neg_hi:[0,0,1]
	v_cvt_pk_bf16_f32 v94, v94, v95
	v_cvt_pk_bf16_f32 v95, v96, v97
	v_cvt_pk_bf16_f32 v90, v90, v91
	v_cvt_pk_bf16_f32 v91, v92, v93
	global_store_dwordx2 v215, v[94:95], s[42:43]
	global_store_dwordx2 v212, v[90:91], s[42:43]
	v_pk_mul_f32 v[218:219], v[82:83], v[170:171]
	v_pk_mul_f32 v[216:217], v[86:87], v[170:171]
	v_pk_fma_f32 v[82:83], v[82:83], v[166:167], v[216:217]
	v_pk_fma_f32 v[86:87], v[86:87], v[166:167], v[218:219] neg_lo:[0,0,1] neg_hi:[0,0,1]
	v_pk_mul_f32 v[218:219], v[84:85], v[172:173]
	v_pk_mul_f32 v[216:217], v[88:89], v[172:173]
	v_pk_fma_f32 v[84:85], v[84:85], v[168:169], v[216:217]
	v_pk_fma_f32 v[88:89], v[88:89], v[168:169], v[218:219] neg_lo:[0,0,1] neg_hi:[0,0,1]
	v_cvt_pk_bf16_f32 v86, v86, v87
	v_cvt_pk_bf16_f32 v87, v88, v89
	v_cvt_pk_bf16_f32 v82, v82, v83
	v_cvt_pk_bf16_f32 v83, v84, v85
	global_store_dwordx2 v215, v[86:87], s[42:43] offset:256
	global_store_dwordx2 v212, v[82:83], s[42:43] offset:256
	s_add_u32 s42, s42, s10
	s_addc_u32 s43, s43, 0
	s_waitcnt vmcnt(20)
	v_pk_mul_f32 v[218:219], v[74:75], v[178:179]
	v_pk_mul_f32 v[216:217], v[78:79], v[178:179]
	v_pk_fma_f32 v[74:75], v[74:75], v[174:175], v[216:217]
	v_pk_fma_f32 v[78:79], v[78:79], v[174:175], v[218:219] neg_lo:[0,0,1] neg_hi:[0,0,1]
	v_pk_mul_f32 v[218:219], v[76:77], v[180:181]
	v_pk_mul_f32 v[216:217], v[80:81], v[180:181]
	v_pk_fma_f32 v[76:77], v[76:77], v[176:177], v[216:217]
	v_pk_fma_f32 v[80:81], v[80:81], v[176:177], v[218:219] neg_lo:[0,0,1] neg_hi:[0,0,1]
	v_cvt_pk_bf16_f32 v78, v78, v79
	v_cvt_pk_bf16_f32 v79, v80, v81
	v_cvt_pk_bf16_f32 v74, v74, v75
	v_cvt_pk_bf16_f32 v75, v76, v77
	global_store_dwordx2 v215, v[78:79], s[42:43]
	global_store_dwordx2 v212, v[74:75], s[42:43]
	v_pk_mul_f32 v[218:219], v[66:67], v[178:179]
	v_pk_mul_f32 v[216:217], v[70:71], v[178:179]
	v_pk_fma_f32 v[66:67], v[66:67], v[174:175], v[216:217]
	v_pk_fma_f32 v[70:71], v[70:71], v[174:175], v[218:219] neg_lo:[0,0,1] neg_hi:[0,0,1]
	v_pk_mul_f32 v[218:219], v[68:69], v[180:181]
	v_pk_mul_f32 v[216:217], v[72:73], v[180:181]
	v_pk_fma_f32 v[68:69], v[68:69], v[176:177], v[216:217]
	v_pk_fma_f32 v[72:73], v[72:73], v[176:177], v[218:219] neg_lo:[0,0,1] neg_hi:[0,0,1]
	v_cvt_pk_bf16_f32 v70, v70, v71
	v_cvt_pk_bf16_f32 v71, v72, v73
	v_cvt_pk_bf16_f32 v66, v66, v67
	v_cvt_pk_bf16_f32 v67, v68, v69
	global_store_dwordx2 v215, v[70:71], s[42:43] offset:256
	global_store_dwordx2 v212, v[66:67], s[42:43] offset:256
	s_add_u32 s42, s42, s11
	s_addc_u32 s43, s43, 0
	s_waitcnt vmcnt(22)
	v_pk_mul_f32 v[218:219], v[58:59], v[186:187]
	v_pk_mul_f32 v[216:217], v[62:63], v[186:187]
	v_pk_fma_f32 v[58:59], v[58:59], v[182:183], v[216:217]
	v_pk_fma_f32 v[62:63], v[62:63], v[182:183], v[218:219] neg_lo:[0,0,1] neg_hi:[0,0,1]
	v_pk_mul_f32 v[218:219], v[60:61], v[188:189]
	v_pk_mul_f32 v[216:217], v[64:65], v[188:189]
	v_pk_fma_f32 v[60:61], v[60:61], v[184:185], v[216:217]
	v_pk_fma_f32 v[64:65], v[64:65], v[184:185], v[218:219] neg_lo:[0,0,1] neg_hi:[0,0,1]
	v_cvt_pk_bf16_f32 v62, v62, v63
	v_cvt_pk_bf16_f32 v63, v64, v65
	v_cvt_pk_bf16_f32 v58, v58, v59
	v_cvt_pk_bf16_f32 v59, v60, v61
	global_store_dwordx2 v215, v[62:63], s[42:43]
	global_store_dwordx2 v212, v[58:59], s[42:43]
	v_pk_mul_f32 v[218:219], v[50:51], v[186:187]
	v_pk_mul_f32 v[216:217], v[54:55], v[186:187]
	v_pk_fma_f32 v[50:51], v[50:51], v[182:183], v[216:217]
	v_pk_fma_f32 v[54:55], v[54:55], v[182:183], v[218:219] neg_lo:[0,0,1] neg_hi:[0,0,1]
	v_pk_mul_f32 v[218:219], v[52:53], v[188:189]
	v_pk_mul_f32 v[216:217], v[56:57], v[188:189]
	v_pk_fma_f32 v[52:53], v[52:53], v[184:185], v[216:217]
	v_pk_fma_f32 v[56:57], v[56:57], v[184:185], v[218:219] neg_lo:[0,0,1] neg_hi:[0,0,1]
	v_cvt_pk_bf16_f32 v54, v54, v55
	v_cvt_pk_bf16_f32 v55, v56, v57
	v_cvt_pk_bf16_f32 v50, v50, v51
	v_cvt_pk_bf16_f32 v51, v52, v53
	global_store_dwordx2 v215, v[54:55], s[42:43] offset:256
	global_store_dwordx2 v212, v[50:51], s[42:43] offset:256
	s_add_u32 s42, s42, s10
	s_addc_u32 s43, s43, 0
	s_waitcnt vmcnt(24)
; __device__ __forceinline__ unsigned pk_bf16(float lo, float hi) { const f32x2 v = {lo, hi}; const bf16v2 b = __builtin_convertvector(v, bf16v2); return __builtin_bit_cast(unsigned, b); }
; template <class Epi>
; __device__ __forceinline__ void gemm_phase(const bf16_t* __restrict__ A, const bf16_t* __restrict__ Bt, int M, int N, LAS unsigned char* lds, const Epi& epi, int vcu) {
;     ...
;         if (!have_next) break;
;         brow = nrow; bcol = ncol;
;     __device__ __forceinline__ void operator()(int row, int G, int fq, f32x4 v0, f32x4 v1) const {
;         const int col32 = G * 32;
;         const unsigned ro = (unsigned)row * (unsigned)ld;
;         if (col32 < rope_end) {
;             const int half = hd >> 1, hb = col32 & ~(hd - 1), d0 = ((col32 & (hd - 1)) >> 5) * 16 + fq * 4, pos = row & (SEQ - 1);
;             const unsigned to = (unsigned)(pos * half + d0);
;             const f32x4 c = *(const f32x4*)(cosT + to), s = *(const f32x4*)(sinT + to);
;             const f32x4 o1 = v0 * c - v1 * s, o2 = v1 * c + v0 * s;
;             u32x2 w1, w2; w1.x = pk_bf16(o1[0], o1[1]); w1.y = pk_bf16(o1[2], o1[3]); w2.x = pk_bf16(o2[0], o2[1]); w2.y = pk_bf16(o2[2], o2[3]);
;             *(u32x2*)(out + (ro + (unsigned)(hb + d0))) = w1; *(u32x2*)(out + (ro + (unsigned)(hb + half + d0))) = w2;
	v_pk_mul_f32 v[218:219], v[42:43], v[194:195]
	v_pk_mul_f32 v[216:217], v[46:47], v[194:195]
	v_pk_fma_f32 v[42:43], v[42:43], v[190:191], v[216:217]
	v_pk_fma_f32 v[46:47], v[46:47], v[190:191], v[218:219] neg_lo:[0,0,1] neg_hi:[0,0,1]
	v_pk_mul_f32 v[218:219], v[44:45], v[196:197]
	v_pk_mul_f32 v[216:217], v[48:49], v[196:197]
	v_pk_fma_f32 v[44:45], v[44:45], v[192:193], v[216:217]
	v_pk_fma_f32 v[48:49], v[48:49], v[192:193], v[218:219] neg_lo:[0,0,1] neg_hi:[0,0,1]
	v_cvt_pk_bf16_f32 v46, v46, v47
	v_cvt_pk_bf16_f32 v47, v48, v49
	v_cvt_pk_bf16_f32 v42, v42, v43
	v_cvt_pk_bf16_f32 v43, v44, v45
	global_store_dwordx2 v215, v[46:47], s[42:43]
	global_store_dwordx2 v212, v[42:43], s[42:43]
	v_pk_mul_f32 v[218:219], v[34:35], v[194:195]
	v_pk_mul_f32 v[216:217], v[38:39], v[194:195]
	v_pk_fma_f32 v[34:35], v[34:35], v[190:191], v[216:217]
	v_pk_fma_f32 v[38:39], v[38:39], v[190:191], v[218:219] neg_lo:[0,0,1] neg_hi:[0,0,1]
	v_pk_mul_f32 v[218:219], v[36:37], v[196:197]
	v_pk_mul_f32 v[216:217], v[40:41], v[196:197]
	v_pk_fma_f32 v[36:37], v[36:37], v[192:193], v[216:217]
	v_pk_fma_f32 v[40:41], v[40:41], v[192:193], v[218:219] neg_lo:[0,0,1] neg_hi:[0,0,1]
	v_cvt_pk_bf16_f32 v38, v38, v39
	v_cvt_pk_bf16_f32 v39, v40, v41
	v_cvt_pk_bf16_f32 v34, v34, v35
	v_cvt_pk_bf16_f32 v35, v36, v37
	global_store_dwordx2 v215, v[38:39], s[42:43] offset:256
	global_store_dwordx2 v212, v[34:35], s[42:43] offset:256
	s_add_u32 s42, s42, s10
	s_addc_u32 s43, s43, 0
	s_waitcnt vmcnt(18)
	v_pk_mul_f32 v[218:219], v[26:27], v[154:155]
	v_pk_mul_f32 v[216:217], v[30:31], v[154:155]
	v_pk_fma_f32 v[26:27], v[26:27], v[150:151], v[216:217]
	v_pk_fma_f32 v[30:31], v[30:31], v[150:151], v[218:219] neg_lo:[0,0,1] neg_hi:[0,0,1]
	v_pk_mul_f32 v[218:219], v[28:29], v[156:157]
	v_pk_mul_f32 v[216:217], v[32:33], v[156:157]
	v_pk_fma_f32 v[28:29], v[28:29], v[152:153], v[216:217]
	v_pk_fma_f32 v[32:33], v[32:33], v[152:153], v[218:219] neg_lo:[0,0,1] neg_hi:[0,0,1]
	v_cvt_pk_bf16_f32 v30, v30, v31
	v_cvt_pk_bf16_f32 v31, v32, v33
	v_cvt_pk_bf16_f32 v26, v26, v27
	v_cvt_pk_bf16_f32 v27, v28, v29
	global_store_dwordx2 v215, v[30:31], s[42:43]
	global_store_dwordx2 v212, v[26:27], s[42:43]
	v_pk_mul_f32 v[218:219], v[18:19], v[154:155]
	v_pk_mul_f32 v[216:217], v[22:23], v[154:155]
	v_pk_fma_f32 v[18:19], v[18:19], v[150:151], v[216:217]
	v_pk_fma_f32 v[22:23], v[22:23], v[150:151], v[218:219] neg_lo:[0,0,1] neg_hi:[0,0,1]
	v_pk_mul_f32 v[218:219], v[20:21], v[156:157]
	v_pk_mul_f32 v[216:217], v[24:25], v[156:157]
	v_pk_fma_f32 v[20:21], v[20:21], v[152:153], v[216:217]
	v_pk_fma_f32 v[24:25], v[24:25], v[152:153], v[218:219] neg_lo:[0,0,1] neg_hi:[0,0,1]
	v_cvt_pk_bf16_f32 v22, v22, v23
	v_cvt_pk_bf16_f32 v23, v24, v25
	v_cvt_pk_bf16_f32 v18, v18, v19
	v_cvt_pk_bf16_f32 v19, v20, v21
	global_store_dwordx2 v215, v[22:23], s[42:43] offset:256
	global_store_dwordx2 v212, v[18:19], s[42:43] offset:256
	s_add_u32 s42, s42, s10
	s_addc_u32 s43, s43, 0
	s_waitcnt vmcnt(20)
	v_pk_mul_f32 v[218:219], v[10:11], v[162:163]
	v_pk_mul_f32 v[216:217], v[14:15], v[162:163]
	v_pk_fma_f32 v[10:11], v[10:11], v[158:159], v[216:217]
	v_pk_fma_f32 v[14:15], v[14:15], v[158:159], v[218:219] neg_lo:[0,0,1] neg_hi:[0,0,1]
	v_pk_mul_f32 v[218:219], v[12:13], v[164:165]
	v_pk_mul_f32 v[216:217], v[16:17], v[164:165]
	v_pk_fma_f32 v[12:13], v[12:13], v[160:161], v[216:217]
	v_pk_fma_f32 v[16:17], v[16:17], v[160:161], v[218:219] neg_lo:[0,0,1] neg_hi:[0,0,1]
	v_cvt_pk_bf16_f32 v14, v14, v15
	v_cvt_pk_bf16_f32 v15, v16, v17
	v_cvt_pk_bf16_f32 v10, v10, v11
	v_cvt_pk_bf16_f32 v11, v12, v13
	global_store_dwordx2 v215, v[14:15], s[42:43]
	global_store_dwordx2 v212, v[10:11], s[42:43]
	v_pk_mul_f32 v[218:219], v[2:3], v[162:163]
	v_pk_mul_f32 v[216:217], v[6:7], v[162:163]
	v_pk_fma_f32 v[2:3], v[2:3], v[158:159], v[216:217]
	v_pk_fma_f32 v[6:7], v[6:7], v[158:159], v[218:219] neg_lo:[0,0,1] neg_hi:[0,0,1]
	v_pk_mul_f32 v[218:219], v[4:5], v[164:165]
	v_pk_mul_f32 v[216:217], v[8:9], v[164:165]
	v_pk_fma_f32 v[4:5], v[4:5], v[160:161], v[216:217]
	v_pk_fma_f32 v[8:9], v[8:9], v[160:161], v[218:219] neg_lo:[0,0,1] neg_hi:[0,0,1]
	v_cvt_pk_bf16_f32 v6, v6, v7
	v_cvt_pk_bf16_f32 v7, v8, v9
	v_cvt_pk_bf16_f32 v2, v2, v3
	v_cvt_pk_bf16_f32 v3, v4, v5
	global_store_dwordx2 v215, v[6:7], s[42:43] offset:256
	global_store_dwordx2 v212, v[2:3], s[42:43] offset:256
	s_mov_b32 s83, s12
	s_mov_b32 s70, s13
	s_mov_b32 s36, s86
	s_mov_b32 s86, s87
	s_mov_b32 s87, s92
	s_mov_b64 s[12:13], s[72:73]
	s_mov_b32 s73, s93
	s_movk_i32 s72, 0x1fff
	s_branch .LBB0_251
